# opt14: + compression GEMM loop: 16 loads per wait (was 3 serialized waits per k-step)
# baseline (speedup 1.0000x reference)
; #define MFMA16(a, b, c) __builtin_amdgcn_mfma_f32_16x16x32_f16((a), (b), (c), 0, 0, 0)
; __device__ __forceinline__ void phase_compress(ArgsP a, int layer, unsigned char* lds) {
;     ...
;             for (int k8 = 0; k8 < 64; k8 += 8) {
;                 half8 af[8], bf[8];
; #pragma unroll
;                 for (int u = 0; u < 8; ++u) { const int ks = k8 + u; int tok = 16 * nrow + (ks >> 1); tok = tok < S ? tok : S - 1;
;                     af[u] = *(const half8*)(xcol + (size_t)tok * NPROJ + 32 * (ks & 1)); bf[u] = *(const half8*)(wrow + 32 * ks); }
; #pragma unroll
;                 for (int u = 0; u < 8; ++u) acc = MFMA16(af[u], bf[u], acc);
;             }
;             const float bs = cbias[kv * 64 + 16 * et + c];
; #pragma unroll
;             for (int r = 0; r < 4; ++r) {
;                 const int n = 16 * nb + 4 * g + r, e = 16 * et + c;
;                 const float v = (n == 1023) ? 0.f : acc[r] + bs;
;                 if (kv == 0) kc[(size_t)b * 65536 + (size_t)(n >> 5) * 2048 + ((((n >> 4) & 1) * 2 + (e >> 5)) * 64 + (n & 15) * 4 + ((e >> 3) & 3)) * 8 + (e & 7)] = (half_t)v;
;                 else vct[(size_t)b * 65536 + (size_t)(n >> 5) * 2048 + (e * 4 + ((n & 15) >> 2)) * 8 + (n & 3) + 4 * ((n >> 4) & 1)] = (half_t)v;
.LBB0_593:
	v_min_u32_e32 v0, 0x3fff, v11
	v_mul_u32_u24_e32 v0, 0xa00, v0
	v_add_u32_e32 v9, 1, v11
	v_add_u32_e32 v46, 2, v11
	v_add_u32_e32 v47, 3, v11
	v_lshlrev_b32_e32 v0, 1, v0
	v_min_u32_e32 v9, 0x3fff, v9
	v_min_u32_e32 v46, 0x3fff, v46
	v_min_u32_e32 v47, 0x3fff, v47
	v_lshl_add_u64 v[50:51], v[14:15], 0, v[0:1]
	flat_load_dwordx4 v[64:67], v[12:13]
	flat_load_dwordx4 v[68:71], v[12:13] offset:64
	flat_load_dwordx4 v[72:75], v[12:13] offset:128
	flat_load_dwordx4 v[76:79], v[12:13] offset:192
	flat_load_dwordx4 v[80:83], v[12:13] offset:256
	flat_load_dwordx4 v[84:87], v[12:13] offset:320
	flat_load_dwordx4 v[88:91], v[12:13] offset:384
	flat_load_dwordx4 v[92:95], v[12:13] offset:448
	v_mul_u32_u24_e32 v9, 0xa00, v9
	v_mul_u32_u24_e32 v54, 0xa00, v46
	v_mul_u32_u24_e32 v60, 0xa00, v47
	flat_load_dwordx4 v[96:99], v[50:51]
	flat_load_dwordx4 v[100:103], v[50:51] offset:64
	v_lshlrev_b32_e32 v0, 1, v9
	v_lshl_add_u64 v[58:59], v[14:15], 0, v[0:1]
	flat_load_dwordx4 v[104:107], v[58:59]
	flat_load_dwordx4 v[108:111], v[58:59] offset:64
	v_lshlrev_b32_e32 v0, 1, v54
	v_lshl_add_u64 v[46:47], v[14:15], 0, v[0:1]
	flat_load_dwordx4 v[112:115], v[46:47]
	flat_load_dwordx4 v[116:119], v[46:47] offset:64
	v_lshlrev_b32_e32 v0, 1, v60
	v_lshl_add_u64 v[46:47], v[14:15], 0, v[0:1]
	flat_load_dwordx4 v[120:123], v[46:47]
	flat_load_dwordx4 v[124:127], v[46:47] offset:64
	s_add_i32 s9, s9, 8
	s_mov_b64 s[10:11], 0x200
	v_add_u32_e32 v11, 4, v11
	v_lshl_add_u64 v[12:13], v[12:13], 0, s[10:11]
	s_cmp_gt_u32 s9, 55
	s_waitcnt vmcnt(0) lgkmcnt(0)
	v_mfma_f32_16x16x32_f16 v[2:5], v[96:99], v[64:67], v[2:5]
	v_mfma_f32_16x16x32_f16 v[2:5], v[100:103], v[68:71], v[2:5]
	v_mfma_f32_16x16x32_f16 v[2:5], v[104:107], v[72:75], v[2:5]
	v_mfma_f32_16x16x32_f16 v[2:5], v[108:111], v[76:79], v[2:5]
	v_mfma_f32_16x16x32_f16 v[2:5], v[112:115], v[80:83], v[2:5]
	v_mfma_f32_16x16x32_f16 v[2:5], v[116:119], v[84:87], v[2:5]
	v_mfma_f32_16x16x32_f16 v[2:5], v[120:123], v[88:91], v[2:5]
	v_mfma_f32_16x16x32_f16 v[2:5], v[124:127], v[92:95], v[2:5]
	s_cbranch_scc0 .LBB0_593
	s_lshl_b32 s22, s18, 4
	s_and_b32 s21, s22, 48
	v_or_b32_e32 v11, s21, v18
	v_or_b32_e32 v0, s8, v11
	v_lshlrev_b32_e32 v0, 2, v0
	v_lshl_add_u64 v[12:13], s[6:7], 0, v[0:1]
	flat_load_dword v9, v[12:13]
	s_cmpk_gt_u32 s18, 0x1ff
	s_cselect_b64 s[8:9], -1, 0
	s_and_b32 s10, s18, 4
	s_lshl_b32 s11, s5, 17
	s_add_u32 s5, s16, s11
	s_addc_u32 s23, s17, 0
	s_and_b32 s24, s4, 0x1f000
	s_add_u32 s4, s5, s24
	v_lshl_or_b32 v0, v11, 6, v8
	s_addc_u32 s5, s23, 0
	s_lshl_b32 s84, s10, 1
	v_lshl_add_u64 v[12:13], s[4:5], 0, v[0:1]
	s_add_u32 s4, s14, s11
	s_addc_u32 s5, s15, 0
	s_add_u32 s4, s4, s24
	v_lshl_add_u64 v[12:13], v[12:13], 0, s[84:85]
	s_addc_u32 s5, s5, 0
	s_mov_b64 s[10:11], -1
	s_and_b64 vcc, exec, s[8:9]
	s_waitcnt vmcnt(0) lgkmcnt(0)
	v_add_f32_e32 v0, v2, v9
	v_cvt_f16_f32_e32 v2, v0
	s_cbranch_vccz .LBB0_596
	flat_store_short v[12:13], v2
	s_mov_b64 s[10:11], 0
